# scan out-tile store: running base + immediate offsets instead of 16 separate 64-bit address computations
# speedup vs baseline: 1.0061x; 1.0005x over previous
.LBB0_573:
	s_add_i32 s46, s44, 1
	v_min_i32_e32 v20, s46, v181
	v_sub_u32_e32 v21, v181, v20
	v_cndmask_b32_e64 v20, v21, v20, s[18:19]
	v_lshl_add_u32 v20, v20, 6, v183
	v_ashrrev_i32_e32 v21, 31, v20
	v_lshl_add_u64 v[22:23], v[20:21], 1, v[206:207]
	global_load_dwordx4 v[54:57], v[22:23], off
	v_ashrrev_i32_e32 v22, 6, v20
	v_ashrrev_i32_e32 v23, 31, v22
	v_lshlrev_b64 v[24:25], 9, v[22:23]
	v_lshl_add_u64 v[24:25], v[208:209], 0, v[24:25]
	v_lshlrev_b64 v[20:21], 8, v[20:21]
	global_load_dword v187, v[24:25], off
	v_lshl_add_u64 v[24:25], v[210:211], 0, v[20:21]
	s_movk_i32 s45, 0x2000
	v_add_co_u32_e32 v26, vcc, s45, v24
	s_movk_i32 s47, 0x3000
	s_nop 0
	v_addc_co_u32_e32 v27, vcc, 0, v25, vcc
	global_load_dwordx4 v[58:61], v[24:25], off
	v_add_co_u32_e32 v24, vcc, s47, v24
	v_lshl_add_u64 v[20:21], v[212:213], 0, v[20:21]
	s_nop 0
	v_addc_co_u32_e32 v25, vcc, 0, v25, vcc
	global_load_dwordx4 v[70:73], v[26:27], off offset:-4096
	global_load_dwordx4 v[74:77], v[26:27], off
	global_load_dwordx4 v[82:85], v[24:25], off
	global_load_dwordx4 v[90:93], v[20:21], off
	v_add_co_u32_e32 v24, vcc, s45, v20
	v_add_u32_e32 v158, v163, v150
	s_nop 0
	v_addc_co_u32_e32 v25, vcc, 0, v21, vcc
	v_add_co_u32_e32 v20, vcc, s47, v20
	global_load_dwordx4 v[94:97], v[24:25], off offset:-4096
	global_load_dwordx4 v[98:101], v[24:25], off
	v_addc_co_u32_e32 v21, vcc, 0, v21, vcc
	global_load_dwordx4 v[102:105], v[20:21], off
	v_lshl_add_u64 v[20:21], v[2:3], 0, v[22:23]
	v_lshlrev_b64 v[20:21], 14, v[20:21]
	v_lshl_or_b32 v20, v198, 7, v20
	v_lshl_add_u64 v[20:21], v[152:153], 0, v[20:21]
	global_load_dwordx4 v[86:89], v[20:21], off
	global_load_dwordx4 v[78:81], v[20:21], off offset:32
	global_load_dwordx4 v[66:69], v[20:21], off offset:64
	global_load_dwordx4 v[62:65], v[20:21], off offset:96
	s_waitcnt lgkmcnt(0)
	s_barrier
	ds_read_b128 v[106:109], v173 offset:28160
	ds_read_b128 v[234:237], v158 offset:45568
	ds_read_b128 v[110:113], v173 offset:28192
	ds_read_b128 v[238:241], v158 offset:45600
	ds_read_b128 v[134:137], v173 offset:28224
	ds_read_b128 v[242:245], v158 offset:45632
	ds_read_b128 v[114:117], v173 offset:28256
	ds_read_b128 v[246:249], v158 offset:45664
	ds_read_b128 v[118:121], v173 offset:28288
	ds_read_b128 v[250:253], v158 offset:45696
	ds_read_b128 v[122:125], v173 offset:28320
	ds_read_b128 v[126:129], v173 offset:28352
	ds_read_b128 v[130:133], v173 offset:28384
	s_and_b32 s45, s44, 1
	s_mul_i32 s47, s45, 0x1200
	v_add_u32_e32 v189, s47, v154
	v_add3_u32 v189, v189, v165, v150
	s_waitcnt lgkmcnt(11)
	v_mfma_f32_32x32x16_bf16 v[20:35], v[106:109], v[234:237], 0
	ds_read_b128 v[234:237], v158 offset:45728
	s_waitcnt lgkmcnt(10)
	v_mfma_f32_32x32x16_bf16 v[20:35], v[110:113], v[238:241], v[20:35]
	ds_read_b128 v[238:241], v158 offset:45760
	s_waitcnt lgkmcnt(9)
	v_mfma_f32_32x32x16_bf16 v[20:35], v[134:137], v[242:245], v[20:35]
	ds_read_b128 v[242:245], v158 offset:45792
	s_waitcnt lgkmcnt(8)
	v_mfma_f32_32x32x16_bf16 v[20:35], v[114:117], v[246:249], v[20:35]
	s_waitcnt lgkmcnt(6)
	v_mfma_f32_32x32x16_bf16 v[20:35], v[118:121], v[250:253], v[20:35]
	s_waitcnt lgkmcnt(2)
	v_mfma_f32_32x32x16_bf16 v[20:35], v[122:125], v[234:237], v[20:35]
	s_waitcnt lgkmcnt(1)
	v_mfma_f32_32x32x16_bf16 v[20:35], v[126:129], v[238:241], v[20:35]
	s_waitcnt lgkmcnt(0)
	v_mfma_f32_32x32x16_bf16 v[20:35], v[130:133], v[242:245], v[20:35]
	s_nop 11
	v_cndmask_b32_e64 v20, 0, v20, s[78:79]
	v_cndmask_b32_e64 v21, 0, v21, s[80:81]
	v_bfe_u32 v158, v20, 16, 1
	v_cndmask_b32_e64 v22, 0, v22, s[82:83]
	v_bfe_u32 v159, v21, 16, 1
	v_add3_u32 v20, v20, v158, s73
	v_add3_u32 v21, v21, v159, s73
	ds_write_b16_d16_hi v175, v20 offset:8704
	ds_write_b16_d16_hi v175, v21 offset:8848
	v_bfe_u32 v20, v22, 16, 1
	v_add3_u32 v20, v22, v20, s73
	ds_write_b16_d16_hi v175, v20 offset:8992
	v_cndmask_b32_e64 v20, 0, v23, s[84:85]
	v_bfe_u32 v21, v20, 16, 1
	v_add3_u32 v20, v20, v21, s73
	ds_write_b16_d16_hi v175, v20 offset:9136
	v_cndmask_b32_e64 v20, 0, v24, s[86:87]
	v_bfe_u32 v21, v20, 16, 1
	v_add3_u32 v20, v20, v21, s73
	ds_write_b16_d16_hi v175, v20 offset:9856
	v_cndmask_b32_e64 v20, 0, v25, s[88:89]
	v_bfe_u32 v21, v20, 16, 1
	v_add3_u32 v20, v20, v21, s73
	ds_write_b16_d16_hi v175, v20 offset:10000
	v_cndmask_b32_e64 v20, 0, v26, s[90:91]
	v_bfe_u32 v21, v20, 16, 1
	v_add3_u32 v20, v20, v21, s73
	ds_write_b16_d16_hi v175, v20 offset:10144
	v_cndmask_b32_e64 v20, 0, v27, s[92:93]
	v_bfe_u32 v21, v20, 16, 1
	v_add3_u32 v20, v20, v21, s73
	ds_write_b16_d16_hi v175, v20 offset:10288
	v_cndmask_b32_e64 v20, 0, v28, s[94:95]
	v_bfe_u32 v21, v20, 16, 1
	v_add3_u32 v20, v20, v21, s73
	ds_write_b16_d16_hi v175, v20 offset:11008
	v_cndmask_b32_e64 v20, 0, v29, s[96:97]
	v_bfe_u32 v21, v20, 16, 1
	v_add3_u32 v20, v20, v21, s73
	ds_write_b16_d16_hi v175, v20 offset:11152
	v_cndmask_b32_e64 v20, 0, v30, s[16:17]
	v_bfe_u32 v21, v20, 16, 1
	v_add3_u32 v20, v20, v21, s73
	ds_write_b16_d16_hi v175, v20 offset:11296
	v_cndmask_b32_e64 v20, 0, v31, s[8:9]
	v_bfe_u32 v21, v20, 16, 1
	v_add3_u32 v20, v20, v21, s73
	ds_write_b16_d16_hi v175, v20 offset:11440
	v_cndmask_b32_e64 v20, 0, v32, s[0:1]
	v_bfe_u32 v21, v20, 16, 1
	v_add3_u32 v20, v20, v21, s73
	ds_write_b16_d16_hi v175, v20 offset:12160
	v_cndmask_b32_e64 v20, 0, v33, s[10:11]
	v_bfe_u32 v21, v20, 16, 1
	v_add3_u32 v20, v20, v21, s73
	ds_write_b16_d16_hi v175, v20 offset:12304
	v_cndmask_b32_e64 v20, 0, v34, s[12:13]
	v_bfe_u32 v21, v20, 16, 1
	v_add3_u32 v20, v20, v21, s73
	ds_write_b16_d16_hi v175, v20 offset:12448
	v_cndmask_b32_e64 v20, 0, v35, s[14:15]
	v_bfe_u32 v21, v20, 16, 1
	v_add3_u32 v20, v20, v21, s73
	ds_write_b16_d16_hi v175, v20 offset:12592
	s_waitcnt lgkmcnt(0)
	s_barrier
	s_and_saveexec_b64 vcc, s[6:7]
	s_cbranch_execz .LBB0_575
	v_mov_b32_e32 v20, s44
	v_cndmask_b32_e64 v20, v185, v20, s[18:19]
	v_lshl_add_u32 v230, v20, 6, v183
	ds_read_b128 v[234:237], v169
	ds_read_b128 v[238:241], v169 offset:32
	ds_read_b128 v[242:245], v169 offset:64
	ds_read_b128 v[246:249], v169 offset:96
	ds_read_b128 v[250:253], v169 offset:128
	ds_read_b128 v[158:161], v169 offset:160
	v_ashrrev_i32_e32 v231, 31, v230
	s_waitcnt lgkmcnt(5)
	v_mfma_f32_32x32x16_bf16 v[20:35], v[106:109], v[234:237], 0
	ds_read_b128 v[106:109], v169 offset:192
	ds_read_b128 v[234:237], v177 offset:8704
	s_waitcnt lgkmcnt(6)
	v_mfma_f32_32x32x16_bf16 v[20:35], v[110:113], v[238:241], v[20:35]
	ds_read_b128 v[110:113], v169 offset:224
	ds_read_b128 v[238:241], v189 offset:17920
	s_waitcnt lgkmcnt(7)
	v_mfma_f32_32x32x16_bf16 v[20:35], v[134:137], v[242:245], v[20:35]
	ds_read_b128 v[242:245], v177 offset:8736
	ds_read_b128 v[134:137], v189 offset:17952
	s_waitcnt lgkmcnt(8)
	v_mfma_f32_32x32x16_bf16 v[20:35], v[114:117], v[246:249], v[20:35]
	ds_read_b128 v[246:249], v177 offset:8768
	ds_read_b128 v[114:117], v189 offset:17984
	s_waitcnt lgkmcnt(9)
	v_mfma_f32_32x32x16_bf16 v[20:35], v[118:121], v[250:253], v[20:35]
	ds_read_b128 v[250:253], v177 offset:8800
	ds_read_b128 v[118:121], v189 offset:18016
	s_waitcnt lgkmcnt(10)
	v_mfma_f32_32x32x16_bf16 v[20:35], v[122:125], v[158:161], v[20:35]
	s_waitcnt lgkmcnt(9)
	v_mfma_f32_32x32x16_bf16 v[20:35], v[126:129], v[106:109], v[20:35]
	s_waitcnt lgkmcnt(7)
	v_mfma_f32_32x32x16_bf16 v[20:35], v[130:133], v[110:113], v[20:35]
	s_waitcnt lgkmcnt(6)
	v_mfma_f32_32x32x16_bf16 v[20:35], v[234:237], v[238:241], v[20:35]
	s_waitcnt lgkmcnt(4)
	v_mfma_f32_32x32x16_bf16 v[20:35], v[242:245], v[134:137], v[20:35]
	s_waitcnt lgkmcnt(2)
	v_mfma_f32_32x32x16_bf16 v[20:35], v[246:249], v[114:117], v[20:35]
	s_waitcnt lgkmcnt(0)
	v_mfma_f32_32x32x16_bf16 v[20:35], v[250:253], v[118:121], v[20:35]
	v_lshl_add_u64 v[106:107], v[214:215], 0, v[230:231]
	v_mov_b32_e32 v109, v107
	s_nop 9
	v_bfe_u32 v108, v20, 16, 1
	v_add3_u32 v20, v20, v108, s73
	v_or_b32_e32 v108, v106, v162
	v_lshlrev_b64 v[108:109], 11, v[108:109]
	v_lshl_add_u64 v[108:109], v[216:217], 0, v[108:109]
	v_mov_b64_e32 v[158:159], v[108:109]
	s_mov_b64 s[98:99], 0x1000
	v_mov_b32_e32 v160, 0x3000
	v_mov_b32_e32 v161, 0
	global_store_short_d16_hi v[108:109], v20, off
	v_bfe_u32 v20, v21, 16, 1
	v_add3_u32 v108, v21, v20, s73
	global_store_short_d16_hi v[158:159], v108, off offset:2048
	v_bfe_u32 v20, v22, 16, 1
	v_add3_u32 v22, v22, v20, s73
	v_lshl_add_u64 v[158:159], v[158:159], 0, s[98:99]
	global_store_short_d16_hi v[158:159], v22, off
	v_bfe_u32 v20, v23, 16, 1
	v_add3_u32 v22, v23, v20, s73
	global_store_short_d16_hi v[158:159], v22, off offset:2048
	v_bfe_u32 v20, v24, 16, 1
	v_add3_u32 v22, v24, v20, s73
	v_lshl_add_u64 v[158:159], v[158:159], 0, v[160:161]
	global_store_short_d16_hi v[158:159], v22, off
	v_bfe_u32 v20, v25, 16, 1
	v_add3_u32 v22, v25, v20, s73
	global_store_short_d16_hi v[158:159], v22, off offset:2048
	v_bfe_u32 v20, v26, 16, 1
	v_add3_u32 v22, v26, v20, s73
	v_lshl_add_u64 v[158:159], v[158:159], 0, s[98:99]
	global_store_short_d16_hi v[158:159], v22, off
	v_bfe_u32 v20, v27, 16, 1
	v_add3_u32 v22, v27, v20, s73
	global_store_short_d16_hi v[158:159], v22, off offset:2048
	v_bfe_u32 v20, v28, 16, 1
	v_add3_u32 v22, v28, v20, s73
	v_lshl_add_u64 v[158:159], v[158:159], 0, v[160:161]
	global_store_short_d16_hi v[158:159], v22, off
	v_bfe_u32 v20, v29, 16, 1
	v_add3_u32 v22, v29, v20, s73
	global_store_short_d16_hi v[158:159], v22, off offset:2048
	v_bfe_u32 v20, v30, 16, 1
	v_add3_u32 v22, v30, v20, s73
	v_lshl_add_u64 v[158:159], v[158:159], 0, s[98:99]
	global_store_short_d16_hi v[158:159], v22, off
	v_bfe_u32 v20, v31, 16, 1
	v_add3_u32 v22, v31, v20, s73
	global_store_short_d16_hi v[158:159], v22, off offset:2048
	v_bfe_u32 v20, v32, 16, 1
	v_add3_u32 v22, v32, v20, s73
	v_lshl_add_u64 v[158:159], v[158:159], 0, v[160:161]
	global_store_short_d16_hi v[158:159], v22, off
	v_bfe_u32 v20, v33, 16, 1
	v_add3_u32 v22, v33, v20, s73
	global_store_short_d16_hi v[158:159], v22, off offset:2048
	v_bfe_u32 v20, v34, 16, 1
	v_add3_u32 v22, v34, v20, s73
	v_lshl_add_u64 v[158:159], v[158:159], 0, s[98:99]
	global_store_short_d16_hi v[158:159], v22, off
	v_bfe_u32 v20, v35, 16, 1
	v_add3_u32 v22, v35, v20, s73
	global_store_short_d16_hi v[158:159], v22, off offset:2048
